# instruction selection: replace 6-hop ds_bpermute butterfly by DPP quad_perm/row_mirror + permlane16/32_swap reduction in the four shw_gemm loops (bit-identical sums)
# speedup vs baseline: 1.0065x; 1.0018x over previous
.LBB0_189:
	v_add_u32_e32 v25, s15, v76
	ds_read_b128 v[102:105], v25
	ds_read_b128 v[106:109], v25 offset:16
	ds_read_b128 v[110:113], v25 offset:2048
	ds_read_b128 v[114:117], v25 offset:2064
	ds_read_b128 v[118:121], v25 offset:4096
	ds_read_b128 v[122:125], v25 offset:4112
	ds_read_b128 v[126:129], v25 offset:6144
	ds_read_b128 v[130:133], v25 offset:6160
	s_waitcnt lgkmcnt(7)
	v_mov_b32_e32 v134, v103
	v_mov_b32_e32 v135, v104
	v_mov_b32_e32 v103, v105
	s_waitcnt lgkmcnt(6)
	v_mov_b32_e32 v104, v106
	s_waitcnt lgkmcnt(5)
	v_mov_b32_e32 v106, v111
	v_mov_b32_e32 v111, v113
	v_mov_b32_e32 v105, v108
	v_mov_b32_e32 v108, v107
	v_mov_b32_e32 v107, v112
	s_waitcnt lgkmcnt(4)
	v_mov_b32_e32 v112, v114
	v_mov_b32_e32 v113, v116
	v_mov_b32_e32 v116, v115
	s_waitcnt lgkmcnt(0)
	v_mul_f32_e32 v115, v132, v21
	v_mul_f32_e32 v114, v119, v65
	v_pk_mul_f32 v[102:103], v[102:103], v[48:49]
	v_pk_mul_f32 v[110:111], v[110:111], v[56:57]
	v_mul_f32_e32 v25, v128, v17
	v_mov_b32_e32 v128, v122
	v_mul_f32_e32 v122, v121, v67
	v_pk_mul_f32 v[108:109], v[108:109], v[54:55]
	v_pk_mul_f32 v[116:117], v[116:117], v[62:63]
	v_pk_fma_f32 v[118:119], v[118:119], v[64:65], v[114:115] op_sel_hi:[1,1,0]
	v_pk_fma_f32 v[102:103], v[134:135], v[50:51], v[102:103]
	v_pk_fma_f32 v[106:107], v[106:107], v[58:59], v[110:111]
	v_mul_f32_e32 v27, v129, v19
	v_mov_b32_e32 v129, v126
	v_mov_b32_e32 v126, v123
	v_pk_fma_f32 v[120:121], v[120:121], v[66:67], v[122:123] op_sel_hi:[1,1,0]
	v_pk_fma_f32 v[104:105], v[104:105], v[52:53], v[108:109]
	v_pk_fma_f32 v[108:109], v[112:113], v[60:61], v[116:117]
	v_mov_b32_e32 v119, v25
	v_add_f32_e32 v25, v102, v103
	v_pk_add_f32 v[102:103], v[106:107], v[106:107] op_sel:[0,1] op_sel_hi:[1,0]
	v_mul_f32_e32 v29, v133, v23
	v_mov_b32_e32 v132, v124
	v_mov_b32_e32 v133, v130
	v_mov_b32_e32 v130, v125
	v_pk_mul_f32 v[124:125], v[126:127], v[70:71]
	v_mov_b32_e32 v121, v27
	v_add_f32_e32 v25, v25, v104
	v_pk_add_f32 v[102:103], v[102:103], v[108:109]
	v_pk_mul_f32 v[122:123], v[130:131], v[74:75]
	v_pk_fma_f32 v[110:111], v[128:129], v[68:69], v[124:125]
	v_pk_add_f32 v[106:107], v[118:119], v[120:121]
	v_add_f32_e32 v25, v105, v25
	v_pk_add_f32 v[102:103], v[108:109], v[102:103] op_sel:[1,0] op_sel_hi:[0,1]
	v_pk_fma_f32 v[112:113], v[132:133], v[72:73], v[122:123]
	v_pk_add_f32 v[106:107], v[110:111], v[106:107]
	v_add_f32_e32 v114, 0, v25
	v_mov_b32_e32 v103, v29
	v_pk_add_f32 v[104:105], v[106:107], v[112:113]
	v_pk_add_f32 v[102:103], v[114:115], v[102:103]
	v_cmp_eq_u32_e64 s[0:1], s15, v77
	v_pk_add_f32 v[102:103], v[102:103], v[104:105]
	s_addk_i32 s15, 0x2000
	v_add_f32_e32 v25, v102, v103
	s_cmp_lg_u32 s15, 0x20000
	s_nop 1
	v_add_f32_dpp v25, v25, v25 quad_perm:[1,0,3,2] row_mask:0xf bank_mask:0xf
	s_nop 1
	v_add_f32_dpp v25, v25, v25 quad_perm:[2,3,0,1] row_mask:0xf bank_mask:0xf
	s_nop 1
	v_add_f32_dpp v25, v25, v25 row_half_mirror row_mask:0xf bank_mask:0xf
	s_nop 1
	v_add_f32_dpp v25, v25, v25 row_mirror row_mask:0xf bank_mask:0xf
	v_mov_b32_e32 v27, v25
	s_nop 1
	v_permlane16_swap_b32 v27, v25
	s_nop 1
	v_add_f32_e32 v25, v27, v25
	v_mov_b32_e32 v27, v25
	s_nop 1
	v_permlane32_swap_b32 v27, v25
	s_nop 1
	v_add_f32_e32 v25, v27, v25
	v_cndmask_b32_e64 v15, v15, v25, s[0:1]
	s_cbranch_scc1 .LBB0_189
	s_and_saveexec_b64 s[0:1], vcc
	s_cbranch_execz .LBB0_187
	v_lshl_add_u64 v[48:49], v[44:45], 2, v[42:43]
	global_store_dword v[48:49], v15, off
	s_branch .LBB0_187

.LBB0_196:
	v_add_u32_e32 v25, s11, v76
	ds_read_b128 v[102:105], v25
	ds_read_b128 v[106:109], v25 offset:16
	ds_read_b128 v[110:113], v25 offset:2048
	ds_read_b128 v[114:117], v25 offset:2064
	ds_read_b128 v[118:121], v25 offset:4096
	ds_read_b128 v[122:125], v25 offset:4112
	ds_read_b128 v[126:129], v25 offset:6144
	ds_read_b128 v[130:133], v25 offset:6160
	s_waitcnt lgkmcnt(7)
	v_mov_b32_e32 v74, v103
	v_mov_b32_e32 v75, v104
	v_mov_b32_e32 v103, v105
	s_waitcnt lgkmcnt(6)
	v_mov_b32_e32 v104, v106
	v_mov_b32_e32 v105, v108
	v_mov_b32_e32 v108, v107
	s_waitcnt lgkmcnt(5)
	v_mov_b32_e32 v106, v111
	v_mov_b32_e32 v111, v113
	v_mov_b32_e32 v107, v112
	s_waitcnt lgkmcnt(4)
	v_mov_b32_e32 v112, v114
	v_mov_b32_e32 v113, v116
	v_mov_b32_e32 v116, v115
	s_waitcnt lgkmcnt(0)
	v_mul_f32_e32 v115, v132, v21
	v_mul_f32_e32 v114, v119, v63
	v_pk_mul_f32 v[102:103], v[102:103], v[44:45]
	v_pk_mul_f32 v[108:109], v[108:109], v[52:53]
	v_pk_mul_f32 v[110:111], v[110:111], v[54:55]
	v_mul_f32_e32 v25, v128, v17
	v_mov_b32_e32 v128, v122
	v_mul_f32_e32 v122, v121, v65
	v_pk_mul_f32 v[116:117], v[116:117], v[60:61]
	v_pk_fma_f32 v[118:119], v[118:119], v[62:63], v[114:115] op_sel_hi:[1,1,0]
	v_pk_fma_f32 v[74:75], v[74:75], v[48:49], v[102:103]
	v_pk_fma_f32 v[102:103], v[104:105], v[50:51], v[108:109]
	v_pk_fma_f32 v[104:105], v[106:107], v[56:57], v[110:111]
	v_mul_f32_e32 v27, v129, v19
	v_mov_b32_e32 v129, v126
	v_mov_b32_e32 v126, v123
	v_pk_fma_f32 v[120:121], v[120:121], v[64:65], v[122:123] op_sel_hi:[1,1,0]
	v_pk_fma_f32 v[106:107], v[112:113], v[58:59], v[116:117]
	v_mov_b32_e32 v119, v25
	v_add_f32_e32 v25, v74, v75
	v_pk_add_f32 v[74:75], v[104:105], v[104:105] op_sel:[0,1] op_sel_hi:[1,0]
	v_mul_f32_e32 v29, v133, v23
	v_mov_b32_e32 v132, v124
	v_mov_b32_e32 v133, v130
	v_mov_b32_e32 v130, v125
	v_pk_mul_f32 v[124:125], v[126:127], v[68:69]
	v_mov_b32_e32 v121, v27
	v_add_f32_e32 v25, v25, v102
	v_pk_add_f32 v[74:75], v[74:75], v[106:107]
	v_pk_mul_f32 v[122:123], v[130:131], v[72:73]
	v_pk_fma_f32 v[108:109], v[128:129], v[66:67], v[124:125]
	v_pk_add_f32 v[104:105], v[118:119], v[120:121]
	v_add_f32_e32 v25, v103, v25
	v_pk_add_f32 v[74:75], v[106:107], v[74:75] op_sel:[1,0] op_sel_hi:[0,1]
	v_pk_fma_f32 v[110:111], v[132:133], v[70:71], v[122:123]
	v_pk_add_f32 v[104:105], v[108:109], v[104:105]
	v_add_f32_e32 v114, 0, v25
	v_mov_b32_e32 v75, v29
	v_pk_add_f32 v[102:103], v[104:105], v[110:111]
	v_pk_add_f32 v[74:75], v[114:115], v[74:75]
	v_cmp_eq_u32_e64 s[0:1], s11, v77
	v_pk_add_f32 v[74:75], v[74:75], v[102:103]
	s_addk_i32 s11, 0x2000
	v_add_f32_e32 v25, v74, v75
	s_cmp_lg_u32 s11, 0x20000
	s_nop 1
	v_add_f32_dpp v25, v25, v25 quad_perm:[1,0,3,2] row_mask:0xf bank_mask:0xf
	s_nop 1
	v_add_f32_dpp v25, v25, v25 quad_perm:[2,3,0,1] row_mask:0xf bank_mask:0xf
	s_nop 1
	v_add_f32_dpp v25, v25, v25 row_half_mirror row_mask:0xf bank_mask:0xf
	s_nop 1
	v_add_f32_dpp v25, v25, v25 row_mirror row_mask:0xf bank_mask:0xf
	v_mov_b32_e32 v27, v25
	s_nop 1
	v_permlane16_swap_b32 v27, v25
	s_nop 1
	v_add_f32_e32 v25, v27, v25
	v_mov_b32_e32 v27, v25
	s_nop 1
	v_permlane32_swap_b32 v27, v25
	s_nop 1
	v_add_f32_e32 v25, v27, v25
	v_cndmask_b32_e64 v15, v15, v25, s[0:1]
	s_cbranch_scc1 .LBB0_196
	s_and_saveexec_b64 s[0:1], vcc
	s_cbranch_execz .LBB0_194
	v_lshl_add_u64 v[44:45], v[42:43], 2, v[38:39]
	global_store_dword v[44:45], v15, off
	s_branch .LBB0_194

.LBB0_203:
	v_add_u32_e32 v25, s11, v76
	ds_read_b128 v[86:89], v25
	ds_read_b128 v[90:93], v25 offset:16
	ds_read_b128 v[94:97], v25 offset:2048
	ds_read_b128 v[98:101], v25 offset:2064
	ds_read_b128 v[102:105], v25 offset:4096
	ds_read_b128 v[106:109], v25 offset:4112
	ds_read_b128 v[110:113], v25 offset:6144
	ds_read_b128 v[114:117], v25 offset:6160
	s_waitcnt lgkmcnt(7)
	v_mov_b32_e32 v74, v87
	v_mov_b32_e32 v75, v88
	v_mov_b32_e32 v87, v89
	s_waitcnt lgkmcnt(6)
	v_mov_b32_e32 v88, v90
	v_mov_b32_e32 v89, v92
	v_mov_b32_e32 v92, v91
	s_waitcnt lgkmcnt(5)
	v_mov_b32_e32 v90, v95
	v_mov_b32_e32 v95, v97
	v_mov_b32_e32 v91, v96
	s_waitcnt lgkmcnt(4)
	v_mov_b32_e32 v96, v98
	v_mov_b32_e32 v97, v100
	v_mov_b32_e32 v100, v99
	s_waitcnt lgkmcnt(0)
	v_mul_f32_e32 v99, v116, v21
	v_mul_f32_e32 v98, v103, v63
	v_pk_mul_f32 v[86:87], v[86:87], v[44:45]
	v_pk_mul_f32 v[92:93], v[92:93], v[52:53]
	v_pk_mul_f32 v[94:95], v[94:95], v[54:55]
	v_mul_f32_e32 v25, v112, v17
	v_mov_b32_e32 v112, v106
	v_mul_f32_e32 v106, v105, v65
	v_pk_mul_f32 v[100:101], v[100:101], v[60:61]
	v_pk_fma_f32 v[102:103], v[102:103], v[62:63], v[98:99] op_sel_hi:[1,1,0]
	v_pk_fma_f32 v[74:75], v[74:75], v[48:49], v[86:87]
	v_pk_fma_f32 v[86:87], v[88:89], v[50:51], v[92:93]
	v_pk_fma_f32 v[88:89], v[90:91], v[56:57], v[94:95]
	v_mul_f32_e32 v27, v113, v19
	v_mov_b32_e32 v113, v110
	v_mov_b32_e32 v110, v107
	v_pk_fma_f32 v[104:105], v[104:105], v[64:65], v[106:107] op_sel_hi:[1,1,0]
	v_pk_fma_f32 v[90:91], v[96:97], v[58:59], v[100:101]
	v_mov_b32_e32 v103, v25
	v_add_f32_e32 v25, v74, v75
	v_pk_add_f32 v[74:75], v[88:89], v[88:89] op_sel:[0,1] op_sel_hi:[1,0]
	v_mul_f32_e32 v29, v117, v23
	v_mov_b32_e32 v116, v108
	v_mov_b32_e32 v117, v114
	v_mov_b32_e32 v114, v109
	v_pk_mul_f32 v[108:109], v[110:111], v[68:69]
	v_mov_b32_e32 v105, v27
	v_add_f32_e32 v25, v25, v86
	v_pk_add_f32 v[74:75], v[74:75], v[90:91]
	v_pk_mul_f32 v[106:107], v[114:115], v[72:73]
	v_pk_fma_f32 v[92:93], v[112:113], v[66:67], v[108:109]
	v_pk_add_f32 v[88:89], v[102:103], v[104:105]
	v_add_f32_e32 v25, v87, v25
	v_pk_add_f32 v[74:75], v[90:91], v[74:75] op_sel:[1,0] op_sel_hi:[0,1]
	v_pk_fma_f32 v[94:95], v[116:117], v[70:71], v[106:107]
	v_pk_add_f32 v[88:89], v[92:93], v[88:89]
	v_add_f32_e32 v98, 0, v25
	v_mov_b32_e32 v75, v29
	v_pk_add_f32 v[86:87], v[88:89], v[94:95]
	v_pk_add_f32 v[74:75], v[98:99], v[74:75]
	v_cmp_eq_u32_e64 s[0:1], s11, v77
	v_pk_add_f32 v[74:75], v[74:75], v[86:87]
	s_addk_i32 s11, 0x2000
	v_add_f32_e32 v25, v74, v75
	s_cmp_lg_u32 s11, 0x20000
	s_nop 1
	v_add_f32_dpp v25, v25, v25 quad_perm:[1,0,3,2] row_mask:0xf bank_mask:0xf
	s_nop 1
	v_add_f32_dpp v25, v25, v25 quad_perm:[2,3,0,1] row_mask:0xf bank_mask:0xf
	s_nop 1
	v_add_f32_dpp v25, v25, v25 row_half_mirror row_mask:0xf bank_mask:0xf
	s_nop 1
	v_add_f32_dpp v25, v25, v25 row_mirror row_mask:0xf bank_mask:0xf
	v_mov_b32_e32 v27, v25
	s_nop 1
	v_permlane16_swap_b32 v27, v25
	s_nop 1
	v_add_f32_e32 v25, v27, v25
	v_mov_b32_e32 v27, v25
	s_nop 1
	v_permlane32_swap_b32 v27, v25
	s_nop 1
	v_add_f32_e32 v25, v27, v25
	v_cndmask_b32_e64 v15, v15, v25, s[0:1]
	s_cbranch_scc1 .LBB0_203
	s_and_saveexec_b64 s[0:1], vcc
	s_cbranch_execz .LBB0_201
	v_lshl_add_u64 v[44:45], v[42:43], 2, v[40:41]
	global_store_dword v[44:45], v15, off
	s_branch .LBB0_201

.LBB0_210:
	v_add_u32_e32 v44, s11, v76
	ds_read_b128 v[48:51], v44
	ds_read_b128 v[52:55], v44 offset:16
	ds_read_b128 v[56:59], v44 offset:2048
	ds_read_b128 v[60:63], v44 offset:2064
	ds_read_b128 v[64:67], v44 offset:4096
	ds_read_b128 v[68:71], v44 offset:4112
	ds_read_b128 v[72:75], v44 offset:6144
	ds_read_b128 v[78:81], v44 offset:6160
	s_waitcnt lgkmcnt(7)
	v_mov_b32_e32 v44, v49
	v_mov_b32_e32 v45, v50
	v_mov_b32_e32 v49, v51
	s_waitcnt lgkmcnt(6)
	v_mov_b32_e32 v50, v52
	v_mov_b32_e32 v51, v54
	v_mov_b32_e32 v54, v53
	s_waitcnt lgkmcnt(5)
	v_mov_b32_e32 v52, v57
	v_mov_b32_e32 v57, v59
	v_mov_b32_e32 v53, v58
	s_waitcnt lgkmcnt(4)
	v_mov_b32_e32 v58, v60
	v_mov_b32_e32 v59, v62
	v_mov_b32_e32 v62, v61
	s_waitcnt lgkmcnt(1)
	v_mul_f32_e32 v82, v74, v40
	s_waitcnt lgkmcnt(0)
	v_mul_f32_e32 v61, v80, v42
	v_mov_b32_e32 v74, v68
	v_mul_f32_e32 v60, v65, v23
	v_mul_f32_e32 v68, v67, v25
	v_pk_mul_f32 v[48:49], v[48:49], v[6:7]
	v_pk_mul_f32 v[54:55], v[54:55], v[12:13]
	v_pk_mul_f32 v[56:57], v[56:57], v[14:15]
	v_mul_f32_e32 v83, v75, v41
	v_mov_b32_e32 v75, v72
	v_mov_b32_e32 v72, v69
	v_pk_mul_f32 v[62:63], v[62:63], v[20:21]
	v_pk_fma_f32 v[64:65], v[64:65], v[22:23], v[60:61] op_sel_hi:[1,1,0]
	v_pk_fma_f32 v[66:67], v[66:67], v[24:25], v[68:69] op_sel_hi:[1,1,0]
	v_pk_fma_f32 v[44:45], v[44:45], v[8:9], v[48:49]
	v_pk_fma_f32 v[48:49], v[50:51], v[10:11], v[54:55]
	v_pk_fma_f32 v[50:51], v[52:53], v[16:17], v[56:57]
	v_mul_f32_e32 v84, v81, v43
	v_mov_b32_e32 v80, v70
	v_mov_b32_e32 v81, v78
	v_mov_b32_e32 v78, v71
	v_pk_mul_f32 v[70:71], v[72:73], v[28:29]
	v_pk_fma_f32 v[52:53], v[58:59], v[18:19], v[62:63]
	v_mov_b32_e32 v65, v82
	v_mov_b32_e32 v67, v83
	v_add_f32_e32 v58, v44, v45
	v_pk_add_f32 v[44:45], v[50:51], v[50:51] op_sel:[0,1] op_sel_hi:[1,0]
	v_pk_fma_f32 v[54:55], v[74:75], v[26:27], v[70:71]
	v_pk_add_f32 v[50:51], v[64:65], v[66:67]
	v_add_f32_e32 v48, v58, v48
	v_pk_add_f32 v[44:45], v[44:45], v[52:53]
	v_pk_mul_f32 v[68:69], v[78:79], v[32:33]
	v_pk_add_f32 v[50:51], v[54:55], v[50:51]
	v_add_f32_e32 v54, v49, v48
	v_pk_add_f32 v[44:45], v[52:53], v[44:45] op_sel:[1,0] op_sel_hi:[0,1]
	v_pk_fma_f32 v[56:57], v[80:81], v[30:31], v[68:69]
	v_add_f32_e32 v60, 0, v54
	v_mov_b32_e32 v45, v84
	v_pk_add_f32 v[48:49], v[50:51], v[56:57]
	v_pk_add_f32 v[44:45], v[60:61], v[44:45]
	v_cmp_eq_u32_e64 s[0:1], s11, v77
	v_pk_add_f32 v[44:45], v[44:45], v[48:49]
	s_addk_i32 s11, 0x2000
	v_add_f32_e32 v44, v44, v45
	s_cmp_lg_u32 s11, 0x20000
	s_nop 1
	v_add_f32_dpp v44, v44, v44 quad_perm:[1,0,3,2] row_mask:0xf bank_mask:0xf
	s_nop 1
	v_add_f32_dpp v44, v44, v44 quad_perm:[2,3,0,1] row_mask:0xf bank_mask:0xf
	s_nop 1
	v_add_f32_dpp v44, v44, v44 row_half_mirror row_mask:0xf bank_mask:0xf
	s_nop 1
	v_add_f32_dpp v44, v44, v44 row_mirror row_mask:0xf bank_mask:0xf
	v_mov_b32_e32 v45, v44
	s_nop 1
	v_permlane16_swap_b32 v45, v44
	s_nop 1
	v_add_f32_e32 v44, v45, v44
	v_mov_b32_e32 v45, v44
	s_nop 1
	v_permlane32_swap_b32 v45, v44
	s_nop 1
	v_add_f32_e32 v44, v45, v44
	v_cndmask_b32_e64 v39, v39, v44, s[0:1]
	s_cbranch_scc1 .LBB0_210
	s_and_saveexec_b64 s[0:1], vcc
	s_cbranch_execz .LBB0_208
	v_lshl_add_u64 v[6:7], v[46:47], 2, v[2:3]
	global_store_dword v[6:7], v39, off
	s_branch .LBB0_208
